# P1: last three output pieces per lane kept in spare VGPRs and stored from inside the next K-loop
# baseline (speedup 1.0000x reference)
.LBB0_169:
	s_mov_b64 s[20:21], 0x80
	s_and_b32 s1, s1, 3
	s_add_i32 m0, s72, 0x18000
	v_lshl_add_u64 v[8:9], v[8:9], 0, s[20:21]
	s_lshl_b32 s76, s0, 6
	s_lshl_b32 s5, s0, 13
	s_lshl_b32 s7, s1, 12
	s_waitcnt vmcnt(2)
	s_barrier
	global_load_lds_dwordx4 v[8:9], off
	v_lshl_add_u64 v[6:7], v[6:7], 0, s[20:21]
	s_add_i32 m0, s72, 0x1a000
	s_add_i32 s77, s72, 0x8000
	s_add_i32 s78, s72, 0xa000
	global_load_lds_dwordx4 v[6:7], off
	v_lshl_add_u64 v[2:3], v[2:3], 0, s[20:21]
	s_mov_b32 m0, s77
	s_add_u32 s30, s64, 0x40080
	global_load_lds_dwordx4 v[2:3], off
	v_lshl_add_u64 v[2:3], v[4:5], 0, s[20:21]
	s_mov_b32 m0, s78
	s_addc_u32 s31, s65, 0
	global_load_lds_dwordx4 v[2:3], off
	s_add_i32 m0, s72, 0x1c000
	v_lshl_add_u64 v[2:3], s[30:31], 0, v[132:133]
	global_load_lds_dwordx4 v[2:3], off
	v_lshl_add_u64 v[2:3], s[30:31], 0, v[136:137]
	s_add_i32 m0, s72, 0x1e000
	v_bfe_u32 v157, v10, 4, 2
	global_load_lds_dwordx4 v[2:3], off
	v_and_b32_e32 v156, 15, v10
	v_lshlrev_b32_e32 v2, 4, v157
	v_lshlrev_b32_e32 v3, 2, v10
	v_lshl_or_b32 v2, v156, 6, v2
	v_and_b32_e32 v3, 32, v3
	v_bitop3_b32 v4, v2, s5, v3 bitop3:0xde
	v_bitop3_b32 v158, v2, s7, v3 bitop3:0xde
	v_lshlrev_b32_e32 v2, 14, v11
	v_and_b32_e32 v2, 0xffff8000, v2
	v_lshl_add_u32 v2, v12, 11, v2
	v_and_b32_e32 v3, 1, v11
	s_cmpk_lt_u32 s6, 0x100
	v_lshl_or_b32 v2, v3, 6, v2
	s_cselect_b64 s[44:45], -1, 0
	s_lshl_b32 s79, s1, 6
	s_ashr_i32 s1, s0, 31
	v_lshl_add_u32 v140, v13, 1, v2
	v_lshlrev_b32_e32 v2, 14, v14
	s_lshl_b64 s[0:1], s[0:1], 11
	v_and_b32_e32 v2, 0xffff8000, v2
	s_waitcnt vmcnt(6)
	s_add_u32 s80, s70, s0
	v_lshl_add_u32 v2, v15, 11, v2
	v_and_b32_e32 v3, 1, v14
	s_addc_u32 s81, s71, s1
	v_lshl_or_b32 v2, v3, 6, v2
	s_add_i32 s85, 0, 0x10000
	s_add_i32 s86, 0, 0x14000
	s_ashr_i32 s82, s3, 31
	s_ashr_i32 s83, s2, 31
	v_mov_b32_e32 v141, v139
	v_lshl_add_u32 v142, v16, 1, v2
	v_mov_b32_e32 v143, v139
	v_mov_b64_e32 v[144:145], 0x1200
	v_mov_b64_e32 v[146:147], 0x11ff
	s_movk_i32 s84, 0x241
	v_add_u32_e32 v159, s85, v158
	v_add_u32_e32 v160, s86, v158
	v_add_u32_e32 v161, 0, v4
	s_mov_b32 s46, 0x3e38aa3b
	v_mbcnt_hi_u32_b32 v162, -1, v1
	s_mov_b32 s98, 0
	s_mov_b32 s99, 3
	s_mov_b32 s87, 0
	s_barrier
	s_branch .LBB0_172

.LBB0_175:
	ds_read_b128 v[148:151], v159
	ds_read_b128 v[152:155], v159 offset:1024
	ds_read_b128 v[164:167], v159 offset:2048
	ds_read_b128 v[168:171], v159 offset:3072
	ds_read_b128 v[172:175], v160
	ds_read_b128 v[176:179], v160 offset:1024
	ds_read_b128 v[180:183], v160 offset:2048
	ds_read_b128 v[184:187], v160 offset:3072
	s_add_u32 s6, s60, 0xfffc0080
	s_addc_u32 s7, s61, -1
	s_cmp_eq_u32 s63, 12
	s_cselect_b32 s67, s5, s7
	s_cselect_b32 s66, s8, s6
	s_cselect_b32 s65, s30, s55
	s_cselect_b32 s64, s31, s49
	v_lshl_add_u64 v[220:221], s[60:61], 0, v[140:141]
	s_add_i32 m0, s72, 0xc000
	ds_read_b128 v[188:191], v161
	ds_read_b128 v[192:195], v161 offset:1024
	ds_read_b128 v[196:199], v161 offset:2048
	ds_read_b128 v[200:203], v161 offset:3072
	ds_read_b128 v[204:207], v161 offset:4096
	ds_read_b128 v[208:211], v161 offset:5120
	ds_read_b128 v[212:215], v161 offset:6144
	ds_read_b128 v[216:219], v161 offset:7168
	global_load_lds_dwordx4 v[220:221], off
	v_lshl_add_u64 v[220:221], s[60:61], 0, v[142:143]
	s_add_i32 m0, s72, 0xe000
	s_nop 0
	global_load_lds_dwordx4 v[220:221], off
	s_waitcnt vmcnt(8)
	s_waitcnt lgkmcnt(0)
	s_barrier
	s_setprio 1
	s_waitcnt lgkmcnt(0)
	v_mfma_f32_16x16x32_bf16 v[126:129], v[148:151], v[188:191], v[126:129]
	v_mfma_f32_16x16x32_bf16 v[122:125], v[164:167], v[188:191], v[122:125]
	v_mfma_f32_16x16x32_bf16 v[110:113], v[148:151], v[196:199], v[110:113]
	v_mfma_f32_16x16x32_bf16 v[106:109], v[164:167], v[196:199], v[106:109]
	v_mfma_f32_16x16x32_bf16 v[94:97], v[148:151], v[204:207], v[94:97]
	v_mfma_f32_16x16x32_bf16 v[90:93], v[164:167], v[204:207], v[90:93]
	v_mfma_f32_16x16x32_bf16 v[78:81], v[148:151], v[212:215], v[78:81]
	v_mfma_f32_16x16x32_bf16 v[74:77], v[164:167], v[212:215], v[74:77]
	v_mfma_f32_16x16x32_bf16 v[126:129], v[152:155], v[192:195], v[126:129]
	v_mfma_f32_16x16x32_bf16 v[122:125], v[168:171], v[192:195], v[122:125]
	v_mfma_f32_16x16x32_bf16 v[110:113], v[152:155], v[200:203], v[110:113]
	v_mfma_f32_16x16x32_bf16 v[106:109], v[168:171], v[200:203], v[106:109]
	v_mfma_f32_16x16x32_bf16 v[94:97], v[152:155], v[208:211], v[94:97]
	v_mfma_f32_16x16x32_bf16 v[90:93], v[168:171], v[208:211], v[90:93]
	v_mfma_f32_16x16x32_bf16 v[78:81], v[152:155], v[216:219], v[78:81]
	v_mfma_f32_16x16x32_bf16 v[74:77], v[168:171], v[216:219], v[74:77]
	s_setprio 0
	s_setprio 1
	v_mfma_f32_16x16x32_bf16 v[118:121], v[172:175], v[188:191], v[118:121]
	v_mfma_f32_16x16x32_bf16 v[114:117], v[180:183], v[188:191], v[114:117]
	v_mfma_f32_16x16x32_bf16 v[102:105], v[172:175], v[196:199], v[102:105]
	v_mfma_f32_16x16x32_bf16 v[98:101], v[180:183], v[196:199], v[98:101]
	v_mfma_f32_16x16x32_bf16 v[86:89], v[172:175], v[204:207], v[86:89]
	v_mfma_f32_16x16x32_bf16 v[82:85], v[180:183], v[204:207], v[82:85]
	v_mfma_f32_16x16x32_bf16 v[70:73], v[172:175], v[212:215], v[70:73]
	v_mfma_f32_16x16x32_bf16 v[66:69], v[180:183], v[212:215], v[66:69]
	v_mfma_f32_16x16x32_bf16 v[118:121], v[176:179], v[192:195], v[118:121]
	v_mfma_f32_16x16x32_bf16 v[114:117], v[184:187], v[192:195], v[114:117]
	v_mfma_f32_16x16x32_bf16 v[102:105], v[176:179], v[200:203], v[102:105]
	v_mfma_f32_16x16x32_bf16 v[98:101], v[184:187], v[200:203], v[98:101]
	v_mfma_f32_16x16x32_bf16 v[86:89], v[176:179], v[208:211], v[86:89]
	v_mfma_f32_16x16x32_bf16 v[82:85], v[184:187], v[208:211], v[82:85]
	v_mfma_f32_16x16x32_bf16 v[70:73], v[176:179], v[216:219], v[70:73]
	v_mfma_f32_16x16x32_bf16 v[66:69], v[184:187], v[216:219], v[66:69]
	s_setprio 0
	s_barrier
	s_add_i32 s6, s85, s47
	v_lshl_add_u64 v[220:221], s[64:65], 0, v[132:133]
	s_mov_b32 m0, s6
	ds_read_b128 v[188:191], v161 offset:16384
	ds_read_b128 v[192:195], v161 offset:17408
	ds_read_b128 v[196:199], v161 offset:18432
	ds_read_b128 v[200:203], v161 offset:19456
	ds_read_b128 v[204:207], v161 offset:20480
	ds_read_b128 v[208:211], v161 offset:21504
	ds_read_b128 v[212:215], v161 offset:22528
	ds_read_b128 v[216:219], v161 offset:23552
	global_load_lds_dwordx4 v[220:221], off
	s_add_i32 m0, s6, 0x2000
	s_add_u32 s6, s64, 0x40000
	v_lshl_add_u64 v[222:223], s[64:65], 0, v[136:137]
	s_addc_u32 s7, s65, 0
	s_add_i32 s88, s86, s47
	global_load_lds_dwordx4 v[222:223], off
	v_lshl_add_u64 v[224:225], s[6:7], 0, v[132:133]
	s_mov_b32 m0, s88
	v_lshl_add_u64 v[226:227], s[66:67], 0, v[134:135]
	global_load_lds_dwordx4 v[224:225], off
	v_lshl_add_u64 v[224:225], s[6:7], 0, v[136:137]
	s_add_i32 m0, s88, 0x2000
	s_nop 0
	global_load_lds_dwordx4 v[224:225], off
	v_lshl_add_u64 v[224:225], s[66:67], 0, v[130:131]
	s_mov_b32 m0, s72
	s_nop 0
	global_load_lds_dwordx4 v[224:225], off
	s_mov_b32 m0, s73
	s_nop 0
	global_load_lds_dwordx4 v[226:227], off
	s_waitcnt vmcnt(8)
	s_waitcnt lgkmcnt(0)
	s_barrier
	s_setprio 1
	s_waitcnt lgkmcnt(0)
	v_mfma_f32_16x16x32_bf16 v[62:65], v[148:151], v[188:191], v[62:65]
	v_mfma_f32_16x16x32_bf16 v[58:61], v[164:167], v[188:191], v[58:61]
	v_mfma_f32_16x16x32_bf16 v[46:49], v[148:151], v[196:199], v[46:49]
	v_mfma_f32_16x16x32_bf16 v[42:45], v[164:167], v[196:199], v[42:45]
	v_mfma_f32_16x16x32_bf16 v[30:33], v[148:151], v[204:207], v[30:33]
	v_mfma_f32_16x16x32_bf16 v[26:29], v[164:167], v[204:207], v[26:29]
	v_mfma_f32_16x16x32_bf16 v[14:17], v[148:151], v[212:215], v[14:17]
	v_mfma_f32_16x16x32_bf16 v[10:13], v[164:167], v[212:215], v[10:13]
	v_mfma_f32_16x16x32_bf16 v[62:65], v[152:155], v[192:195], v[62:65]
	v_mfma_f32_16x16x32_bf16 v[58:61], v[168:171], v[192:195], v[58:61]
	v_mfma_f32_16x16x32_bf16 v[46:49], v[152:155], v[200:203], v[46:49]
	v_mfma_f32_16x16x32_bf16 v[42:45], v[168:171], v[200:203], v[42:45]
	v_mfma_f32_16x16x32_bf16 v[30:33], v[152:155], v[208:211], v[30:33]
	v_mfma_f32_16x16x32_bf16 v[26:29], v[168:171], v[208:211], v[26:29]
	v_mfma_f32_16x16x32_bf16 v[14:17], v[152:155], v[216:219], v[14:17]
	v_mfma_f32_16x16x32_bf16 v[10:13], v[168:171], v[216:219], v[10:13]
	s_setprio 0
	s_setprio 1
	v_mfma_f32_16x16x32_bf16 v[54:57], v[172:175], v[188:191], v[54:57]
	v_mfma_f32_16x16x32_bf16 v[50:53], v[180:183], v[188:191], v[50:53]
	v_mfma_f32_16x16x32_bf16 v[38:41], v[172:175], v[196:199], v[38:41]
	v_mfma_f32_16x16x32_bf16 v[34:37], v[180:183], v[196:199], v[34:37]
	v_mfma_f32_16x16x32_bf16 v[22:25], v[172:175], v[204:207], v[22:25]
	v_mfma_f32_16x16x32_bf16 v[18:21], v[180:183], v[204:207], v[18:21]
	v_mfma_f32_16x16x32_bf16 v[6:9], v[172:175], v[212:215], v[6:9]
	v_mfma_f32_16x16x32_bf16 v[2:5], v[180:183], v[212:215], v[2:5]
	v_mfma_f32_16x16x32_bf16 v[54:57], v[176:179], v[192:195], v[54:57]
	v_mfma_f32_16x16x32_bf16 v[50:53], v[184:187], v[192:195], v[50:53]
	v_mfma_f32_16x16x32_bf16 v[38:41], v[176:179], v[200:203], v[38:41]
	v_mfma_f32_16x16x32_bf16 v[34:37], v[184:187], v[200:203], v[34:37]
	v_mfma_f32_16x16x32_bf16 v[22:25], v[176:179], v[208:211], v[22:25]
	v_mfma_f32_16x16x32_bf16 v[18:21], v[184:187], v[208:211], v[18:21]
	v_mfma_f32_16x16x32_bf16 v[6:9], v[176:179], v[216:219], v[6:9]
	v_mfma_f32_16x16x32_bf16 v[2:5], v[184:187], v[216:219], v[2:5]
	s_setprio 0
	s_barrier
	s_add_i32 s88, 0, 0x18000
	v_add_u32_e32 v138, s88, v158
	s_add_i32 s89, 0, 0x1c000
	ds_read_b128 v[148:151], v138
	ds_read_b128 v[152:155], v138 offset:1024
	ds_read_b128 v[164:167], v138 offset:2048
	ds_read_b128 v[168:171], v138 offset:3072
	v_add_u32_e32 v138, s89, v158
	ds_read_b128 v[172:175], v138
	ds_read_b128 v[176:179], v138 offset:1024
	ds_read_b128 v[180:183], v138 offset:2048
	ds_read_b128 v[184:187], v138 offset:3072
	s_add_u32 s6, s66, 0x40000
	s_addc_u32 s7, s67, 0
	s_mov_b32 m0, s74
	v_lshl_add_u64 v[228:229], s[6:7], 0, v[130:131]
	ds_read_b128 v[188:191], v161 offset:32768
	ds_read_b128 v[192:195], v161 offset:33792
	ds_read_b128 v[196:199], v161 offset:34816
	ds_read_b128 v[200:203], v161 offset:35840
	ds_read_b128 v[204:207], v161 offset:36864
	ds_read_b128 v[208:211], v161 offset:37888
	ds_read_b128 v[212:215], v161 offset:38912
	ds_read_b128 v[216:219], v161 offset:39936
	global_load_lds_dwordx4 v[228:229], off
	v_lshl_add_u64 v[228:229], s[6:7], 0, v[134:135]
	s_mov_b32 m0, s75
	s_nop 0
	global_load_lds_dwordx4 v[228:229], off
	s_waitcnt vmcnt(8)
	s_waitcnt lgkmcnt(0)
	s_barrier
	s_setprio 1
	s_waitcnt lgkmcnt(0)
	v_mfma_f32_16x16x32_bf16 v[126:129], v[148:151], v[188:191], v[126:129]
	v_mfma_f32_16x16x32_bf16 v[122:125], v[164:167], v[188:191], v[122:125]
	v_mfma_f32_16x16x32_bf16 v[110:113], v[148:151], v[196:199], v[110:113]
	v_mfma_f32_16x16x32_bf16 v[106:109], v[164:167], v[196:199], v[106:109]
	v_mfma_f32_16x16x32_bf16 v[94:97], v[148:151], v[204:207], v[94:97]
	v_mfma_f32_16x16x32_bf16 v[90:93], v[164:167], v[204:207], v[90:93]
	v_mfma_f32_16x16x32_bf16 v[78:81], v[148:151], v[212:215], v[78:81]
	v_mfma_f32_16x16x32_bf16 v[74:77], v[164:167], v[212:215], v[74:77]
	v_mfma_f32_16x16x32_bf16 v[126:129], v[152:155], v[192:195], v[126:129]
	v_mfma_f32_16x16x32_bf16 v[122:125], v[168:171], v[192:195], v[122:125]
	v_mfma_f32_16x16x32_bf16 v[110:113], v[152:155], v[200:203], v[110:113]
	v_mfma_f32_16x16x32_bf16 v[106:109], v[168:171], v[200:203], v[106:109]
	v_mfma_f32_16x16x32_bf16 v[94:97], v[152:155], v[208:211], v[94:97]
	v_mfma_f32_16x16x32_bf16 v[90:93], v[168:171], v[208:211], v[90:93]
	v_mfma_f32_16x16x32_bf16 v[78:81], v[152:155], v[216:219], v[78:81]
	v_mfma_f32_16x16x32_bf16 v[74:77], v[168:171], v[216:219], v[74:77]
	s_setprio 0
	s_setprio 1
	v_mfma_f32_16x16x32_bf16 v[118:121], v[172:175], v[188:191], v[118:121]
	v_mfma_f32_16x16x32_bf16 v[114:117], v[180:183], v[188:191], v[114:117]
	v_mfma_f32_16x16x32_bf16 v[102:105], v[172:175], v[196:199], v[102:105]
	v_mfma_f32_16x16x32_bf16 v[98:101], v[180:183], v[196:199], v[98:101]
	v_mfma_f32_16x16x32_bf16 v[86:89], v[172:175], v[204:207], v[86:89]
	v_mfma_f32_16x16x32_bf16 v[82:85], v[180:183], v[204:207], v[82:85]
	v_mfma_f32_16x16x32_bf16 v[70:73], v[172:175], v[212:215], v[70:73]
	v_mfma_f32_16x16x32_bf16 v[66:69], v[180:183], v[212:215], v[66:69]
	v_mfma_f32_16x16x32_bf16 v[118:121], v[176:179], v[192:195], v[118:121]
	v_mfma_f32_16x16x32_bf16 v[114:117], v[184:187], v[192:195], v[114:117]
	v_mfma_f32_16x16x32_bf16 v[102:105], v[176:179], v[200:203], v[102:105]
	v_mfma_f32_16x16x32_bf16 v[98:101], v[184:187], v[200:203], v[98:101]
	v_mfma_f32_16x16x32_bf16 v[86:89], v[176:179], v[208:211], v[86:89]
	v_mfma_f32_16x16x32_bf16 v[82:85], v[184:187], v[208:211], v[82:85]
	v_mfma_f32_16x16x32_bf16 v[70:73], v[176:179], v[216:219], v[70:73]
	v_mfma_f32_16x16x32_bf16 v[66:69], v[184:187], v[216:219], v[66:69]
	s_setprio 0
	s_barrier
	s_add_i32 s6, s88, s47
	v_lshl_add_u64 v[220:221], v[220:221], 0, s[20:21]
	s_mov_b32 m0, s6
	ds_read_b128 v[188:191], v161 offset:49152
	ds_read_b128 v[192:195], v161 offset:50176
	ds_read_b128 v[196:199], v161 offset:51200
	ds_read_b128 v[200:203], v161 offset:52224
	ds_read_b128 v[204:207], v161 offset:53248
	ds_read_b128 v[208:211], v161 offset:54272
	ds_read_b128 v[212:215], v161 offset:55296
	ds_read_b128 v[216:219], v161 offset:56320
	global_load_lds_dwordx4 v[220:221], off
	s_add_i32 m0, s6, 0x2000
	s_add_u32 s6, s64, 0x40080
	v_lshl_add_u64 v[220:221], v[222:223], 0, s[20:21]
	s_addc_u32 s7, s65, 0
	s_add_i32 s64, s89, s47
	global_load_lds_dwordx4 v[220:221], off
	v_lshl_add_u64 v[220:221], s[6:7], 0, v[132:133]
	s_mov_b32 m0, s64
	s_nop 0
	global_load_lds_dwordx4 v[220:221], off
	v_lshl_add_u64 v[220:221], s[6:7], 0, v[136:137]
	s_add_i32 m0, s64, 0x2000
	s_nop 0
	global_load_lds_dwordx4 v[220:221], off
	v_lshl_add_u64 v[220:221], v[224:225], 0, s[20:21]
	s_mov_b32 m0, s77
	s_nop 0
	global_load_lds_dwordx4 v[220:221], off
	v_lshl_add_u64 v[220:221], v[226:227], 0, s[20:21]
	s_mov_b32 m0, s78
	s_nop 0
	global_load_lds_dwordx4 v[220:221], off
	s_waitcnt vmcnt(8)
	s_waitcnt lgkmcnt(0)
	s_barrier
	s_setprio 1
	s_waitcnt lgkmcnt(0)
	v_mfma_f32_16x16x32_bf16 v[62:65], v[148:151], v[188:191], v[62:65]
	v_mfma_f32_16x16x32_bf16 v[58:61], v[164:167], v[188:191], v[58:61]
	v_mfma_f32_16x16x32_bf16 v[46:49], v[148:151], v[196:199], v[46:49]
	v_mfma_f32_16x16x32_bf16 v[42:45], v[164:167], v[196:199], v[42:45]
	v_mfma_f32_16x16x32_bf16 v[30:33], v[148:151], v[204:207], v[30:33]
	v_mfma_f32_16x16x32_bf16 v[26:29], v[164:167], v[204:207], v[26:29]
	v_mfma_f32_16x16x32_bf16 v[14:17], v[148:151], v[212:215], v[14:17]
	v_mfma_f32_16x16x32_bf16 v[10:13], v[164:167], v[212:215], v[10:13]
	v_mfma_f32_16x16x32_bf16 v[62:65], v[152:155], v[192:195], v[62:65]
	v_mfma_f32_16x16x32_bf16 v[58:61], v[168:171], v[192:195], v[58:61]
	v_mfma_f32_16x16x32_bf16 v[46:49], v[152:155], v[200:203], v[46:49]
	v_mfma_f32_16x16x32_bf16 v[42:45], v[168:171], v[200:203], v[42:45]
	v_mfma_f32_16x16x32_bf16 v[30:33], v[152:155], v[208:211], v[30:33]
	v_mfma_f32_16x16x32_bf16 v[26:29], v[168:171], v[208:211], v[26:29]
	v_mfma_f32_16x16x32_bf16 v[14:17], v[152:155], v[216:219], v[14:17]
	v_mfma_f32_16x16x32_bf16 v[10:13], v[168:171], v[216:219], v[10:13]
	s_setprio 0
	s_setprio 1
	v_mfma_f32_16x16x32_bf16 v[54:57], v[172:175], v[188:191], v[54:57]
	v_mfma_f32_16x16x32_bf16 v[50:53], v[180:183], v[188:191], v[50:53]
	v_mfma_f32_16x16x32_bf16 v[38:41], v[172:175], v[196:199], v[38:41]
	v_mfma_f32_16x16x32_bf16 v[34:37], v[180:183], v[196:199], v[34:37]
	v_mfma_f32_16x16x32_bf16 v[22:25], v[172:175], v[204:207], v[22:25]
	v_mfma_f32_16x16x32_bf16 v[18:21], v[180:183], v[204:207], v[18:21]
	v_mfma_f32_16x16x32_bf16 v[6:9], v[172:175], v[212:215], v[6:9]
	v_mfma_f32_16x16x32_bf16 v[2:5], v[180:183], v[212:215], v[2:5]
	v_mfma_f32_16x16x32_bf16 v[54:57], v[176:179], v[192:195], v[54:57]
	v_mfma_f32_16x16x32_bf16 v[50:53], v[184:187], v[192:195], v[50:53]
	v_mfma_f32_16x16x32_bf16 v[38:41], v[176:179], v[200:203], v[38:41]
	v_mfma_f32_16x16x32_bf16 v[34:37], v[184:187], v[200:203], v[34:37]
	v_mfma_f32_16x16x32_bf16 v[22:25], v[176:179], v[208:211], v[22:25]
	v_mfma_f32_16x16x32_bf16 v[18:21], v[184:187], v[208:211], v[18:21]
	v_mfma_f32_16x16x32_bf16 v[6:9], v[176:179], v[216:219], v[6:9]
	v_mfma_f32_16x16x32_bf16 v[2:5], v[184:187], v[216:219], v[2:5]
	s_setprio 0
	s_barrier
	s_cmp_gt_u32 s99, 2
	s_cbranch_scc0 .Lpk1_go
.Lpk1_back:
	s_add_i32 s63, s63, 2
	s_add_u32 s60, s60, 0x100
	s_addc_u32 s61, s61, 0
	s_add_u32 s49, s49, 0x100
	s_addc_u32 s55, s55, 0
	s_cmp_gt_u32 s63, 13
	s_cbranch_scc0 .LBB0_175

.LBB0_359:
	v_mov_b32_e32 v20, v139
	v_mov_b32_e32 v21, v139
	v_mov_b32_e32 v22, v139
	v_mov_b32_e32 v23, v139
	v_cvt_pk_bf16_f32 v24, v26, v27
	v_cvt_pk_bf16_f32 v25, v30, v31
	v_cvt_pk_bf16_f32 v26, v28, v29
	v_cvt_pk_bf16_f32 v27, v32, v33
	v_mov_b32_e32 v28, v139
	v_mov_b32_e32 v29, v139
	v_mov_b32_dpp v20, v24 row_ror:8 row_mask:0xf bank_mask:0xf
	v_mov_b32_dpp v21, v25 row_ror:8 row_mask:0xf bank_mask:0xf
	v_mov_b32_e32 v30, v139
	v_mov_b32_dpp v22, v26 row_ror:8 row_mask:0xf bank_mask:0xf
	v_mov_b32_e32 v31, v139
	v_mov_b32_dpp v23, v27 row_ror:8 row_mask:0xf bank_mask:0xf
	v_lshl_add_u64 v[18:19], v[34:35], 0, s[62:63]
	v_mov_b32_dpp v28, v36 row_ror:8 row_mask:0xf bank_mask:0xf
	v_mov_b32_dpp v29, v37 row_ror:8 row_mask:0xf bank_mask:0xf
	v_mov_b32_dpp v30, v38 row_ror:8 row_mask:0xf bank_mask:0xf
	v_mov_b32_dpp v31, v39 row_ror:8 row_mask:0xf bank_mask:0xf
	v_cndmask_b32_e64 v20, v20, v36, s[4:5]
	v_cndmask_b32_e64 v21, v21, v37, s[4:5]
	v_cndmask_b32_e64 v22, v22, v38, s[4:5]
	v_cndmask_b32_e64 v23, v23, v39, s[4:5]
	v_cndmask_b32_e64 v24, v24, v28, s[4:5]
	v_cndmask_b32_e64 v25, v25, v29, s[4:5]
	v_cndmask_b32_e64 v26, v26, v30, s[4:5]
	v_cndmask_b32_e64 v27, v27, v31, s[4:5]
	global_store_dwordx4 v[18:19], v[20:23], off nt
	s_bitset1_b32 s98, 28
	s_cmp_lt_i32 s49, 2
	s_mov_b64 s[60:61], -1
	v_lshl_add_u64 v[20:21], v[18:19], 0, s[8:9]
	v_mov_b32_e32 v230, v24
	v_mov_b32_e32 v231, v25
	v_mov_b32_e32 v232, v26
	v_mov_b32_e32 v233, v27
	v_mov_b32_e32 v242, v20
	v_mov_b32_e32 v243, v21
	s_cbranch_scc1 .LBB0_365
	s_cmp_gt_i32 s49, 2
	s_cbranch_scc0 .LBB0_362
	v_mul_f32_e32 v21, 0xbfb8aa3b, v10
	v_mul_f32_e32 v22, 0xbfb8aa3b, v15
	v_exp_f32_e32 v21, v21
	v_exp_f32_e32 v23, v22
	v_mul_f32_e32 v22, 0xbfb8aa3b, v11
	v_exp_f32_e32 v24, v22
	v_add_f32_e32 v21, 1.0, v21
	v_mul_f32_e32 v25, 0xbfb8aa3b, v12
	v_mul_f32_e32 v26, 0xbfb8aa3b, v17
	v_mul_f32_e32 v20, 0xbfb8aa3b, v14
	v_rcp_f32_e32 v22, v21
	v_add_f32_e32 v21, 1.0, v23
	v_add_f32_e32 v23, 1.0, v24
	v_mul_f32_e32 v24, 0xbfb8aa3b, v16
	v_exp_f32_e32 v25, v25
	v_exp_f32_e32 v27, v26
	v_mul_f32_e32 v26, 0xbfb8aa3b, v13
	v_exp_f32_e32 v20, v20
	v_exp_f32_e32 v24, v24
	v_exp_f32_e32 v28, v26
	v_add_f32_e32 v25, 1.0, v25
	v_add_f32_e32 v20, 1.0, v20
	v_add_f32_e32 v24, 1.0, v24
	v_rcp_f32_e32 v26, v25
	v_add_f32_e32 v25, 1.0, v27
	v_add_f32_e32 v27, 1.0, v28
	v_rcp_f32_e32 v20, v20
	v_rcp_f32_e32 v21, v21
	v_rcp_f32_e32 v23, v23
	v_rcp_f32_e32 v24, v24
	v_rcp_f32_e32 v25, v25
	v_rcp_f32_e32 v27, v27
	s_mov_b64 s[60:61], 0

.LBB0_379:
	v_mov_b32_e32 v2, 0
	v_mov_b32_e32 v3, 0
	v_mov_b32_e32 v4, 0
	v_mov_b32_e32 v5, 0
	v_cvt_pk_bf16_f32 v6, v10, v11
	v_cvt_pk_bf16_f32 v7, v14, v15
	v_cvt_pk_bf16_f32 v8, v12, v13
	v_cvt_pk_bf16_f32 v9, v16, v17
	v_mov_b32_e32 v12, 0
	v_mov_b32_e32 v13, 0
	v_mov_b32_dpp v2, v6 row_ror:8 row_mask:0xf bank_mask:0xf
	v_mov_b32_dpp v3, v7 row_ror:8 row_mask:0xf bank_mask:0xf
	v_mov_b32_e32 v14, 0
	v_mov_b32_dpp v4, v8 row_ror:8 row_mask:0xf bank_mask:0xf
	v_mov_b32_e32 v15, 0
	v_mov_b32_dpp v5, v9 row_ror:8 row_mask:0xf bank_mask:0xf
	v_lshl_add_u64 v[10:11], v[18:19], 0, s[62:63]
	v_mov_b32_dpp v12, v20 row_ror:8 row_mask:0xf bank_mask:0xf
	v_mov_b32_dpp v13, v21 row_ror:8 row_mask:0xf bank_mask:0xf
	v_mov_b32_dpp v14, v22 row_ror:8 row_mask:0xf bank_mask:0xf
	v_mov_b32_dpp v15, v23 row_ror:8 row_mask:0xf bank_mask:0xf
	v_cndmask_b32_e64 v2, v2, v20, s[4:5]
	v_cndmask_b32_e64 v3, v3, v21, s[4:5]
	v_cndmask_b32_e64 v4, v4, v22, s[4:5]
	v_cndmask_b32_e64 v5, v5, v23, s[4:5]
	v_cndmask_b32_e64 v6, v6, v12, s[4:5]
	v_cndmask_b32_e64 v7, v7, v13, s[4:5]
	v_cndmask_b32_e64 v8, v8, v14, s[4:5]
	v_cndmask_b32_e64 v9, v9, v15, s[4:5]
	v_mov_b32_e32 v234, v2
	v_mov_b32_e32 v235, v3
	v_mov_b32_e32 v236, v4
	v_mov_b32_e32 v237, v5
	v_mov_b32_e32 v244, v10
	v_mov_b32_e32 v245, v11
	s_andn2_b64 vcc, exec, s[0:1]
	s_mov_b64 s[0:1], -1
	v_lshl_add_u64 v[2:3], v[10:11], 0, s[8:9]
	v_mov_b32_e32 v238, v6
	v_mov_b32_e32 v239, v7
	v_mov_b32_e32 v240, v8
	v_mov_b32_e32 v241, v9
	v_mov_b32_e32 v246, v2
	v_mov_b32_e32 v247, v3
	s_mov_b32 s99, 0
	s_cbranch_vccnz .LBB0_171
	s_andn2_b64 vcc, exec, s[12:13]
	s_cbranch_vccnz .LBB0_170
	s_barrier
	s_branch .LBB0_170
.Lrwp1_first:
	ds_read_b128 v[148:151], v159
	ds_read_b128 v[152:155], v159 offset:1024
	ds_read_b128 v[164:167], v159 offset:2048
	ds_read_b128 v[168:171], v159 offset:3072
	ds_read_b128 v[172:175], v160
	ds_read_b128 v[176:179], v160 offset:1024
	ds_read_b128 v[180:183], v160 offset:2048
	ds_read_b128 v[184:187], v160 offset:3072
	s_add_u32 s6, s60, 0xfffc0080
	s_addc_u32 s7, s61, -1
	s_cmp_eq_u32 s63, 12
	s_cselect_b32 s67, s5, s7
	s_cselect_b32 s66, s8, s6
	s_cselect_b32 s65, s30, s55
	s_cselect_b32 s64, s31, s49
	v_lshl_add_u64 v[220:221], s[60:61], 0, v[140:141]
	s_add_i32 m0, s72, 0xc000
	ds_read_b128 v[188:191], v161
	ds_read_b128 v[192:195], v161 offset:1024
	ds_read_b128 v[196:199], v161 offset:2048
	ds_read_b128 v[200:203], v161 offset:3072
	ds_read_b128 v[204:207], v161 offset:4096
	ds_read_b128 v[208:211], v161 offset:5120
	ds_read_b128 v[212:215], v161 offset:6144
	ds_read_b128 v[216:219], v161 offset:7168
	global_load_lds_dwordx4 v[220:221], off
	v_lshl_add_u64 v[220:221], s[60:61], 0, v[142:143]
	s_add_i32 m0, s72, 0xe000
	s_nop 0
	global_load_lds_dwordx4 v[220:221], off
	s_cmp_eq_u32 s98, 0x1fff0000
	s_cbranch_scc1 .Lrwp1_a13
	s_cmp_eq_u32 s98, 0x1fffffff
	s_cbranch_scc1 .Lrwp1_a29
	s_waitcnt vmcnt(8)
	s_branch .Lrwp1_adone
.Lrwp1_a13:
	s_waitcnt vmcnt(21)
	s_branch .Lrwp1_adone
.Lrwp1_a29:
	s_waitcnt vmcnt(37)
.Lrwp1_adone:
	s_waitcnt lgkmcnt(0)
	s_barrier
	s_setprio 1
	s_waitcnt lgkmcnt(0)
	v_mfma_f32_16x16x32_bf16 v[126:129], v[148:151], v[188:191], 0
	v_mfma_f32_16x16x32_bf16 v[122:125], v[164:167], v[188:191], 0
	v_mfma_f32_16x16x32_bf16 v[110:113], v[148:151], v[196:199], 0
	v_mfma_f32_16x16x32_bf16 v[106:109], v[164:167], v[196:199], 0
	v_mfma_f32_16x16x32_bf16 v[94:97], v[148:151], v[204:207], 0
	v_mfma_f32_16x16x32_bf16 v[90:93], v[164:167], v[204:207], 0
	v_mfma_f32_16x16x32_bf16 v[78:81], v[148:151], v[212:215], 0
	v_mfma_f32_16x16x32_bf16 v[74:77], v[164:167], v[212:215], 0
	v_mfma_f32_16x16x32_bf16 v[126:129], v[152:155], v[192:195], v[126:129]
	v_mfma_f32_16x16x32_bf16 v[122:125], v[168:171], v[192:195], v[122:125]
	v_mfma_f32_16x16x32_bf16 v[110:113], v[152:155], v[200:203], v[110:113]
	v_mfma_f32_16x16x32_bf16 v[106:109], v[168:171], v[200:203], v[106:109]
	v_mfma_f32_16x16x32_bf16 v[94:97], v[152:155], v[208:211], v[94:97]
	v_mfma_f32_16x16x32_bf16 v[90:93], v[168:171], v[208:211], v[90:93]
	v_mfma_f32_16x16x32_bf16 v[78:81], v[152:155], v[216:219], v[78:81]
	v_mfma_f32_16x16x32_bf16 v[74:77], v[168:171], v[216:219], v[74:77]
	s_setprio 0
	s_setprio 1
	v_mfma_f32_16x16x32_bf16 v[118:121], v[172:175], v[188:191], 0
	v_mfma_f32_16x16x32_bf16 v[114:117], v[180:183], v[188:191], 0
	v_mfma_f32_16x16x32_bf16 v[102:105], v[172:175], v[196:199], 0
	v_mfma_f32_16x16x32_bf16 v[98:101], v[180:183], v[196:199], 0
	v_mfma_f32_16x16x32_bf16 v[86:89], v[172:175], v[204:207], 0
	v_mfma_f32_16x16x32_bf16 v[82:85], v[180:183], v[204:207], 0
	v_mfma_f32_16x16x32_bf16 v[70:73], v[172:175], v[212:215], 0
	v_mfma_f32_16x16x32_bf16 v[66:69], v[180:183], v[212:215], 0
	v_mfma_f32_16x16x32_bf16 v[118:121], v[176:179], v[192:195], v[118:121]
	v_mfma_f32_16x16x32_bf16 v[114:117], v[184:187], v[192:195], v[114:117]
	v_mfma_f32_16x16x32_bf16 v[102:105], v[176:179], v[200:203], v[102:105]
	v_mfma_f32_16x16x32_bf16 v[98:101], v[184:187], v[200:203], v[98:101]
	v_mfma_f32_16x16x32_bf16 v[86:89], v[176:179], v[208:211], v[86:89]
	v_mfma_f32_16x16x32_bf16 v[82:85], v[184:187], v[208:211], v[82:85]
	v_mfma_f32_16x16x32_bf16 v[70:73], v[176:179], v[216:219], v[70:73]
	v_mfma_f32_16x16x32_bf16 v[66:69], v[184:187], v[216:219], v[66:69]
	s_setprio 0
	s_barrier
	s_add_i32 s6, s85, s47
	v_lshl_add_u64 v[220:221], s[64:65], 0, v[132:133]
	s_mov_b32 m0, s6
	ds_read_b128 v[188:191], v161 offset:16384
	ds_read_b128 v[192:195], v161 offset:17408
	ds_read_b128 v[196:199], v161 offset:18432
	ds_read_b128 v[200:203], v161 offset:19456
	ds_read_b128 v[204:207], v161 offset:20480
	ds_read_b128 v[208:211], v161 offset:21504
	ds_read_b128 v[212:215], v161 offset:22528
	ds_read_b128 v[216:219], v161 offset:23552
	global_load_lds_dwordx4 v[220:221], off
	s_add_i32 m0, s6, 0x2000
	s_add_u32 s6, s64, 0x40000
	v_lshl_add_u64 v[222:223], s[64:65], 0, v[136:137]
	s_addc_u32 s7, s65, 0
	s_add_i32 s88, s86, s47
	global_load_lds_dwordx4 v[222:223], off
	v_lshl_add_u64 v[224:225], s[6:7], 0, v[132:133]
	s_mov_b32 m0, s88
	v_lshl_add_u64 v[226:227], s[66:67], 0, v[134:135]
	global_load_lds_dwordx4 v[224:225], off
	v_lshl_add_u64 v[224:225], s[6:7], 0, v[136:137]
	s_add_i32 m0, s88, 0x2000
	s_nop 0
	global_load_lds_dwordx4 v[224:225], off
	v_lshl_add_u64 v[224:225], s[66:67], 0, v[130:131]
	s_mov_b32 m0, s72
	s_nop 0
	global_load_lds_dwordx4 v[224:225], off
	s_mov_b32 m0, s73
	s_nop 0
	global_load_lds_dwordx4 v[226:227], off
	s_cmp_eq_u32 s98, 0x1fff0000
	s_cbranch_scc1 .Lrwp1_b13
	s_cmp_eq_u32 s98, 0x1fffffff
	s_cbranch_scc1 .Lrwp1_b29
	s_waitcnt vmcnt(8)
	s_branch .Lrwp1_bdone

.Lrwp1_bdone:
	s_mov_b32 s98, 0
	s_waitcnt lgkmcnt(0)
	s_barrier
	s_setprio 1
	s_waitcnt lgkmcnt(0)
	v_mfma_f32_16x16x32_bf16 v[62:65], v[148:151], v[188:191], 0
	v_mfma_f32_16x16x32_bf16 v[58:61], v[164:167], v[188:191], 0
	v_mfma_f32_16x16x32_bf16 v[46:49], v[148:151], v[196:199], 0
	v_mfma_f32_16x16x32_bf16 v[42:45], v[164:167], v[196:199], 0
	v_mfma_f32_16x16x32_bf16 v[30:33], v[148:151], v[204:207], 0
	v_mfma_f32_16x16x32_bf16 v[26:29], v[164:167], v[204:207], 0
	v_mfma_f32_16x16x32_bf16 v[14:17], v[148:151], v[212:215], 0
	v_mfma_f32_16x16x32_bf16 v[10:13], v[164:167], v[212:215], 0
	v_mfma_f32_16x16x32_bf16 v[62:65], v[152:155], v[192:195], v[62:65]
	v_mfma_f32_16x16x32_bf16 v[58:61], v[168:171], v[192:195], v[58:61]
	v_mfma_f32_16x16x32_bf16 v[46:49], v[152:155], v[200:203], v[46:49]
	v_mfma_f32_16x16x32_bf16 v[42:45], v[168:171], v[200:203], v[42:45]
	v_mfma_f32_16x16x32_bf16 v[30:33], v[152:155], v[208:211], v[30:33]
	v_mfma_f32_16x16x32_bf16 v[26:29], v[168:171], v[208:211], v[26:29]
	v_mfma_f32_16x16x32_bf16 v[14:17], v[152:155], v[216:219], v[14:17]
	v_mfma_f32_16x16x32_bf16 v[10:13], v[168:171], v[216:219], v[10:13]
	s_setprio 0
	s_setprio 1
	v_mfma_f32_16x16x32_bf16 v[54:57], v[172:175], v[188:191], 0
	v_mfma_f32_16x16x32_bf16 v[50:53], v[180:183], v[188:191], 0
	v_mfma_f32_16x16x32_bf16 v[38:41], v[172:175], v[196:199], 0
	v_mfma_f32_16x16x32_bf16 v[34:37], v[180:183], v[196:199], 0
	v_mfma_f32_16x16x32_bf16 v[22:25], v[172:175], v[204:207], 0
	v_mfma_f32_16x16x32_bf16 v[18:21], v[180:183], v[204:207], 0
	v_mfma_f32_16x16x32_bf16 v[6:9], v[172:175], v[212:215], 0
	v_mfma_f32_16x16x32_bf16 v[2:5], v[180:183], v[212:215], 0
	v_mfma_f32_16x16x32_bf16 v[54:57], v[176:179], v[192:195], v[54:57]
	v_mfma_f32_16x16x32_bf16 v[50:53], v[184:187], v[192:195], v[50:53]
	v_mfma_f32_16x16x32_bf16 v[38:41], v[176:179], v[200:203], v[38:41]
	v_mfma_f32_16x16x32_bf16 v[34:37], v[184:187], v[200:203], v[34:37]
	v_mfma_f32_16x16x32_bf16 v[22:25], v[176:179], v[208:211], v[22:25]
	v_mfma_f32_16x16x32_bf16 v[18:21], v[184:187], v[208:211], v[18:21]
	v_mfma_f32_16x16x32_bf16 v[6:9], v[176:179], v[216:219], v[6:9]
	v_mfma_f32_16x16x32_bf16 v[2:5], v[184:187], v[216:219], v[2:5]
	s_setprio 0
	s_barrier
	s_add_i32 s88, 0, 0x18000
	v_add_u32_e32 v138, s88, v158
	s_add_i32 s89, 0, 0x1c000
	ds_read_b128 v[148:151], v138
	ds_read_b128 v[152:155], v138 offset:1024
	ds_read_b128 v[164:167], v138 offset:2048
	ds_read_b128 v[168:171], v138 offset:3072
	v_add_u32_e32 v138, s89, v158
	ds_read_b128 v[172:175], v138
	ds_read_b128 v[176:179], v138 offset:1024
	ds_read_b128 v[180:183], v138 offset:2048
	ds_read_b128 v[184:187], v138 offset:3072
	s_add_u32 s6, s66, 0x40000
	s_addc_u32 s7, s67, 0
	s_mov_b32 m0, s74
	v_lshl_add_u64 v[228:229], s[6:7], 0, v[130:131]
	ds_read_b128 v[188:191], v161 offset:32768
	ds_read_b128 v[192:195], v161 offset:33792
	ds_read_b128 v[196:199], v161 offset:34816
	ds_read_b128 v[200:203], v161 offset:35840
	ds_read_b128 v[204:207], v161 offset:36864
	ds_read_b128 v[208:211], v161 offset:37888
	ds_read_b128 v[212:215], v161 offset:38912
	ds_read_b128 v[216:219], v161 offset:39936
	global_load_lds_dwordx4 v[228:229], off
	v_lshl_add_u64 v[228:229], s[6:7], 0, v[134:135]
	s_mov_b32 m0, s75
	s_nop 0
	global_load_lds_dwordx4 v[228:229], off
	s_waitcnt vmcnt(8)
	s_waitcnt lgkmcnt(0)
	s_barrier
	s_setprio 1
	s_waitcnt lgkmcnt(0)
	v_mfma_f32_16x16x32_bf16 v[126:129], v[148:151], v[188:191], v[126:129]
	v_mfma_f32_16x16x32_bf16 v[122:125], v[164:167], v[188:191], v[122:125]
	v_mfma_f32_16x16x32_bf16 v[110:113], v[148:151], v[196:199], v[110:113]
	v_mfma_f32_16x16x32_bf16 v[106:109], v[164:167], v[196:199], v[106:109]
	v_mfma_f32_16x16x32_bf16 v[94:97], v[148:151], v[204:207], v[94:97]
	v_mfma_f32_16x16x32_bf16 v[90:93], v[164:167], v[204:207], v[90:93]
	v_mfma_f32_16x16x32_bf16 v[78:81], v[148:151], v[212:215], v[78:81]
	v_mfma_f32_16x16x32_bf16 v[74:77], v[164:167], v[212:215], v[74:77]
	v_mfma_f32_16x16x32_bf16 v[126:129], v[152:155], v[192:195], v[126:129]
	v_mfma_f32_16x16x32_bf16 v[122:125], v[168:171], v[192:195], v[122:125]
	v_mfma_f32_16x16x32_bf16 v[110:113], v[152:155], v[200:203], v[110:113]
	v_mfma_f32_16x16x32_bf16 v[106:109], v[168:171], v[200:203], v[106:109]
	v_mfma_f32_16x16x32_bf16 v[94:97], v[152:155], v[208:211], v[94:97]
	v_mfma_f32_16x16x32_bf16 v[90:93], v[168:171], v[208:211], v[90:93]
	v_mfma_f32_16x16x32_bf16 v[78:81], v[152:155], v[216:219], v[78:81]
	v_mfma_f32_16x16x32_bf16 v[74:77], v[168:171], v[216:219], v[74:77]
	s_setprio 0
	s_setprio 1
	v_mfma_f32_16x16x32_bf16 v[118:121], v[172:175], v[188:191], v[118:121]
	v_mfma_f32_16x16x32_bf16 v[114:117], v[180:183], v[188:191], v[114:117]
	v_mfma_f32_16x16x32_bf16 v[102:105], v[172:175], v[196:199], v[102:105]
	v_mfma_f32_16x16x32_bf16 v[98:101], v[180:183], v[196:199], v[98:101]
	v_mfma_f32_16x16x32_bf16 v[86:89], v[172:175], v[204:207], v[86:89]
	v_mfma_f32_16x16x32_bf16 v[82:85], v[180:183], v[204:207], v[82:85]
	v_mfma_f32_16x16x32_bf16 v[70:73], v[172:175], v[212:215], v[70:73]
	v_mfma_f32_16x16x32_bf16 v[66:69], v[180:183], v[212:215], v[66:69]
	v_mfma_f32_16x16x32_bf16 v[118:121], v[176:179], v[192:195], v[118:121]
	v_mfma_f32_16x16x32_bf16 v[114:117], v[184:187], v[192:195], v[114:117]
	v_mfma_f32_16x16x32_bf16 v[102:105], v[176:179], v[200:203], v[102:105]
	v_mfma_f32_16x16x32_bf16 v[98:101], v[184:187], v[200:203], v[98:101]
	v_mfma_f32_16x16x32_bf16 v[86:89], v[176:179], v[208:211], v[86:89]
	v_mfma_f32_16x16x32_bf16 v[82:85], v[184:187], v[208:211], v[82:85]
	v_mfma_f32_16x16x32_bf16 v[70:73], v[176:179], v[216:219], v[70:73]
	v_mfma_f32_16x16x32_bf16 v[66:69], v[184:187], v[216:219], v[66:69]
	s_setprio 0
	s_barrier
	s_add_i32 s6, s88, s47
	v_lshl_add_u64 v[220:221], v[220:221], 0, s[20:21]
	s_mov_b32 m0, s6
	ds_read_b128 v[188:191], v161 offset:49152
	ds_read_b128 v[192:195], v161 offset:50176
	ds_read_b128 v[196:199], v161 offset:51200
	ds_read_b128 v[200:203], v161 offset:52224
	ds_read_b128 v[204:207], v161 offset:53248
	ds_read_b128 v[208:211], v161 offset:54272
	ds_read_b128 v[212:215], v161 offset:55296
	ds_read_b128 v[216:219], v161 offset:56320
	global_load_lds_dwordx4 v[220:221], off
	s_add_i32 m0, s6, 0x2000
	s_add_u32 s6, s64, 0x40080
	v_lshl_add_u64 v[220:221], v[222:223], 0, s[20:21]
	s_addc_u32 s7, s65, 0
	s_add_i32 s64, s89, s47
	global_load_lds_dwordx4 v[220:221], off
	v_lshl_add_u64 v[220:221], s[6:7], 0, v[132:133]
	s_mov_b32 m0, s64
	s_nop 0
	global_load_lds_dwordx4 v[220:221], off
	v_lshl_add_u64 v[220:221], s[6:7], 0, v[136:137]
	s_add_i32 m0, s64, 0x2000
	s_nop 0
	global_load_lds_dwordx4 v[220:221], off
	v_lshl_add_u64 v[220:221], v[224:225], 0, s[20:21]
	s_mov_b32 m0, s77
	s_nop 0
	global_load_lds_dwordx4 v[220:221], off
	v_lshl_add_u64 v[220:221], v[226:227], 0, s[20:21]
	s_mov_b32 m0, s78
	s_nop 0
	global_load_lds_dwordx4 v[220:221], off
	s_waitcnt vmcnt(8)
	s_waitcnt lgkmcnt(0)
	s_barrier
	s_setprio 1
	s_waitcnt lgkmcnt(0)
	v_mfma_f32_16x16x32_bf16 v[62:65], v[148:151], v[188:191], v[62:65]
	v_mfma_f32_16x16x32_bf16 v[58:61], v[164:167], v[188:191], v[58:61]
	v_mfma_f32_16x16x32_bf16 v[46:49], v[148:151], v[196:199], v[46:49]
	v_mfma_f32_16x16x32_bf16 v[42:45], v[164:167], v[196:199], v[42:45]
	v_mfma_f32_16x16x32_bf16 v[30:33], v[148:151], v[204:207], v[30:33]
	v_mfma_f32_16x16x32_bf16 v[26:29], v[164:167], v[204:207], v[26:29]
	v_mfma_f32_16x16x32_bf16 v[14:17], v[148:151], v[212:215], v[14:17]
	v_mfma_f32_16x16x32_bf16 v[10:13], v[164:167], v[212:215], v[10:13]
	v_mfma_f32_16x16x32_bf16 v[62:65], v[152:155], v[192:195], v[62:65]
	v_mfma_f32_16x16x32_bf16 v[58:61], v[168:171], v[192:195], v[58:61]
	v_mfma_f32_16x16x32_bf16 v[46:49], v[152:155], v[200:203], v[46:49]
	v_mfma_f32_16x16x32_bf16 v[42:45], v[168:171], v[200:203], v[42:45]
	v_mfma_f32_16x16x32_bf16 v[30:33], v[152:155], v[208:211], v[30:33]
	v_mfma_f32_16x16x32_bf16 v[26:29], v[168:171], v[208:211], v[26:29]
	v_mfma_f32_16x16x32_bf16 v[14:17], v[152:155], v[216:219], v[14:17]
	v_mfma_f32_16x16x32_bf16 v[10:13], v[168:171], v[216:219], v[10:13]
	s_setprio 0
	s_setprio 1
	v_mfma_f32_16x16x32_bf16 v[54:57], v[172:175], v[188:191], v[54:57]
	v_mfma_f32_16x16x32_bf16 v[50:53], v[180:183], v[188:191], v[50:53]
	v_mfma_f32_16x16x32_bf16 v[38:41], v[172:175], v[196:199], v[38:41]
	v_mfma_f32_16x16x32_bf16 v[34:37], v[180:183], v[196:199], v[34:37]
	v_mfma_f32_16x16x32_bf16 v[22:25], v[172:175], v[204:207], v[22:25]
	v_mfma_f32_16x16x32_bf16 v[18:21], v[180:183], v[204:207], v[18:21]
	v_mfma_f32_16x16x32_bf16 v[6:9], v[172:175], v[212:215], v[6:9]
	v_mfma_f32_16x16x32_bf16 v[2:5], v[180:183], v[212:215], v[2:5]
	v_mfma_f32_16x16x32_bf16 v[54:57], v[176:179], v[192:195], v[54:57]
	v_mfma_f32_16x16x32_bf16 v[50:53], v[184:187], v[192:195], v[50:53]
	v_mfma_f32_16x16x32_bf16 v[38:41], v[176:179], v[200:203], v[38:41]
	v_mfma_f32_16x16x32_bf16 v[34:37], v[184:187], v[200:203], v[34:37]
	v_mfma_f32_16x16x32_bf16 v[22:25], v[176:179], v[208:211], v[22:25]
	v_mfma_f32_16x16x32_bf16 v[18:21], v[184:187], v[208:211], v[18:21]
	v_mfma_f32_16x16x32_bf16 v[6:9], v[176:179], v[216:219], v[6:9]
	v_mfma_f32_16x16x32_bf16 v[2:5], v[184:187], v[216:219], v[2:5]
	s_setprio 0
	s_barrier
	s_add_i32 s63, s63, 2
	s_add_u32 s60, s60, 0x100
	s_addc_u32 s61, s61, 0
	s_add_u32 s49, s49, 0x100
	s_addc_u32 s55, s55, 0
	s_cmp_gt_u32 s63, 13
	s_cbranch_scc0 .LBB0_175
	s_branch .Lrwp1_exit
.Lpk1_go:
	s_cmp_eq_u32 s99, 0
	s_cbranch_scc1 .Lpk1_0
	s_cmp_eq_u32 s99, 1
	s_cbranch_scc1 .Lpk1_1
.Lpk1_2:
	global_store_dwordx4 v[246:247], v[238:241], off nt
	s_branch .Lpk1_upd
.Lpk1_1:
	global_store_dwordx4 v[244:245], v[234:237], off nt
	s_branch .Lpk1_upd
.Lpk1_0:
	global_store_dwordx4 v[242:243], v[230:233], off nt
.Lpk1_upd:
	s_add_i32 s99, s99, 1
	s_branch .Lpk1_back
.LBB0_382:
	global_store_dwordx4 v[242:243], v[230:233], off nt
	global_store_dwordx4 v[244:245], v[234:237], off nt
	global_store_dwordx4 v[246:247], v[238:241], off nt
	s_mov_b32 s99, 3
	s_waitcnt vmcnt(0)
	v_readlane_b32 s86, v249, 2
	v_readlane_b32 s87, v249, 3
	s_barrier
